# sgu weight-fragment and bias loads issued together; pool input rows loaded together
# speedup vs baseline: 1.0147x; 1.0026x over previous
; DI void seq_bounds(int t, int& s0, int& S) { if (t < T_PROMPT) { S = 16384; s0 = t & ~16383; } else { S = 4096; s0 = T_PROMPT + ((t - T_PROMPT) & ~4095); } }
; DI void pool_task(const Params& p, int layer, int tile, unsigned char* lds) {
;     ...
;   const int g = wid, half = 1 << g, t0 = tile * 64; int s0, S; seq_bounds(t0, s0, S);
;   bf16_t* proj = (bf16_t*)(p.ws + WS_PROJ);
;   bf16_t* xs = (bf16_t*)lds + g * 80 * 72;
;   for (int i = 0; i < 10; ++i) {
;     const int c = lane + 64 * i, rr = c >> 3, dc = (c & 7) * 8, t = t0 - 8 + rr;
;     u32x4 v = {0u, 0u, 0u, 0u};
;     if (t >= s0 && t < s0 + S) v = *(const u32x4*)(proj + (size_t)t * PP + D_X + 64 * g + dc);
;     *(u32x4*)(xs + rr * 72 + dc) = v;
;   }
.LBB0_116:
	s_cmpk_gt_i32 s4, 0xbff
	s_mov_b64 s[0:1], -1
	s_cbranch_scc0 .LBB0_182
	s_cmpk_gt_u32 s4, 0xeff
	s_cbranch_scc0 .LBB0_179
	s_cmpk_gt_u32 s4, 0x14ff
	s_cbranch_scc0 .LBB0_174
	s_add_i32 s0, s4, 0xffffeb00
	s_lshl_b32 s34, s0, 6
	s_cmpk_lt_u32 s0, 0x200
	s_mov_b32 s0, 0xf000
	v_mov_b32_e32 v100, v180
	s_cselect_b32 s0, 0xc000, s0
	s_cselect_b32 s21, s30, 0x1000
	s_and_b32 s35, s0, s34
	s_add_i32 s7, s34, -8
	v_bfe_u32 v9, v100, 3, 3
	v_lshlrev_b32_e32 v0, 3, v100
	s_add_i32 s6, s35, s21
	v_and_b32_e32 v1, 56, v0
	v_and_b32_e32 v88, 0xffffffc0, v100
	v_ashrrev_i32_e32 v89, 31, v88
	v_lshlrev_b32_e32 v6, 1, v1
	v_ashrrev_i32_e32 v102, 6, v100
	s_movk_i32 s0, 0x2d00
	v_mul_lo_u32 v8, v102, s0
	v_add_u32_e32 v54, 0, v8
	v_lshl_add_u32 v10, v1, 1, v54
	v_mul_u32_u24_e32 v4, 0x90, v9
	v_add_u32_e32 v10, v4, v10
	v_or_b32_e32 v7, s7, v9
	v_add_u32_e32 v5, 8, v7
	s_movk_i32 s2, 0xc40
	v_mul_lo_u32 v160, v5, s2
	v_lshl_add_u64 v[226:227], v[160:161], 1, s[46:47]
	v_lshl_add_u64 v[226:227], v[88:89], 1, v[226:227]
	v_mov_b32_e32 v228, v6
	v_mov_b32_e32 v229, v161
	v_lshl_add_u64 v[226:227], v[226:227], 0, v[228:229]
	v_add_co_u32_e32 v226, vcc, 0x1000, v226
	s_nop 1
	v_addc_co_u32_e32 v227, vcc, 0, v227, vcc
	v_subrev_co_u32_e32 v226, vcc, 0xc400, v226
	s_nop 1
	v_subbrev_co_u32_e32 v227, vcc, 0, v227, vcc
	v_add_u32_e32 v4, 0, v7
	v_cmp_le_i32_e32 vcc, s35, v4
	v_cmp_gt_i32_e64 s[0:1], s6, v4
	v_mov_b32_e32 v116, 0
	v_mov_b32_e32 v117, 0
	v_mov_b32_e32 v118, 0
	v_mov_b32_e32 v119, 0
	s_and_b64 s[0:1], vcc, s[0:1]
	s_and_saveexec_b64 s[8:9], s[0:1]
	s_cbranch_execz .Lpoolin_0
	global_load_dwordx4 v[116:119], v[226:227], off offset:1024
.Lpoolin_0:
	s_or_b64 exec, exec, s[8:9]
	v_add_co_u32_e32 v226, vcc, 0xc400, v226
	s_nop 1
	v_addc_co_u32_e32 v227, vcc, 0, v227, vcc
	v_add_u32_e32 v4, 8, v7
	v_cmp_le_i32_e32 vcc, s35, v4
	v_cmp_gt_i32_e64 s[0:1], s6, v4
	v_mov_b32_e32 v120, 0
	v_mov_b32_e32 v121, 0
	v_mov_b32_e32 v122, 0
	v_mov_b32_e32 v123, 0
	s_and_b64 s[0:1], vcc, s[0:1]
	s_and_saveexec_b64 s[8:9], s[0:1]
	s_cbranch_execz .Lpoolin_1
	global_load_dwordx4 v[120:123], v[226:227], off offset:1024
.Lpoolin_1:
	s_or_b64 exec, exec, s[8:9]
	v_add_co_u32_e32 v226, vcc, 0xc400, v226
	s_nop 1
	v_addc_co_u32_e32 v227, vcc, 0, v227, vcc
	v_add_u32_e32 v4, 16, v7
	v_cmp_le_i32_e32 vcc, s35, v4
	v_cmp_gt_i32_e64 s[0:1], s6, v4
	v_mov_b32_e32 v124, 0
	v_mov_b32_e32 v125, 0
	v_mov_b32_e32 v126, 0
	v_mov_b32_e32 v127, 0
	s_and_b64 s[0:1], vcc, s[0:1]
	s_and_saveexec_b64 s[8:9], s[0:1]
	s_cbranch_execz .Lpoolin_2
	global_load_dwordx4 v[124:127], v[226:227], off offset:1024
.Lpoolin_2:
	s_or_b64 exec, exec, s[8:9]
	v_add_co_u32_e32 v226, vcc, 0xc400, v226
	s_nop 1
	v_addc_co_u32_e32 v227, vcc, 0, v227, vcc
	v_add_u32_e32 v4, 24, v7
	v_cmp_le_i32_e32 vcc, s35, v4
	v_cmp_gt_i32_e64 s[0:1], s6, v4
	v_mov_b32_e32 v128, 0
	v_mov_b32_e32 v129, 0
	v_mov_b32_e32 v130, 0
	v_mov_b32_e32 v131, 0
	s_and_b64 s[0:1], vcc, s[0:1]
	s_and_saveexec_b64 s[8:9], s[0:1]
	s_cbranch_execz .Lpoolin_3
	global_load_dwordx4 v[128:131], v[226:227], off offset:1024
.Lpoolin_3:
	s_or_b64 exec, exec, s[8:9]
	v_add_co_u32_e32 v226, vcc, 0xc400, v226
	s_nop 1
	v_addc_co_u32_e32 v227, vcc, 0, v227, vcc
	v_add_u32_e32 v4, 32, v7
	v_cmp_le_i32_e32 vcc, s35, v4
	v_cmp_gt_i32_e64 s[0:1], s6, v4
	v_mov_b32_e32 v132, 0
	v_mov_b32_e32 v133, 0
	v_mov_b32_e32 v134, 0
	v_mov_b32_e32 v135, 0
	s_and_b64 s[0:1], vcc, s[0:1]
	s_and_saveexec_b64 s[8:9], s[0:1]
	s_cbranch_execz .Lpoolin_4
	global_load_dwordx4 v[132:135], v[226:227], off offset:1024
; DI void pool_task(const Params& p, int layer, int tile, unsigned char* lds) {
;     ...
;   for (int i = 0; i < 10; ++i) {
;     const int c = lane + 64 * i, rr = c >> 3, dc = (c & 7) * 8, t = t0 - 8 + rr;
;     u32x4 v = {0u, 0u, 0u, 0u};
;     if (t >= s0 && t < s0 + S) v = *(const u32x4*)(proj + (size_t)t * PP + D_X + 64 * g + dc);
;     *(u32x4*)(xs + rr * 72 + dc) = v;
;   }
;   __syncthreads();
;   f32x16 acc[2][2];
; #pragma unroll
;   for (int a = 0; a < 2; ++a)
; #pragma unroll
;     for (int b = 0; b < 2; ++b)
; #pragma unroll
;       for (int i = 0; i < 16; ++i) acc[a][b][i] = 0.f;
;   const bf16_t* WT = (const bf16_t*)(p.ws + WS_POOLW) + (size_t)(layer * 4 + g) * 4096;
; #pragma unroll
;   for (int mt = 0; mt < 2; ++mt) {
;     const int tl = 32 * mt + r, pos = t0 + tl - s0;
;     const int lo = max(pos - half, 0), hi = min(pos + half, S);
;     const float inv = 1.f / (float)(hi - lo);
; #pragma unroll
;     for (int ks = 0; ks < 4; ++ks) {
;       float sum[8];
; #pragma unroll
;       for (int e = 0; e < 8; ++e) sum[e] = 0.f;
;       for (int w = 0; w < 2 * half; ++w) {
.Lpoolin_4:
	s_or_b64 exec, exec, s[8:9]
	v_add_co_u32_e32 v226, vcc, 0xc400, v226
	s_nop 1
	v_addc_co_u32_e32 v227, vcc, 0, v227, vcc
	v_add_u32_e32 v4, 40, v7
	v_cmp_le_i32_e32 vcc, s35, v4
	v_cmp_gt_i32_e64 s[0:1], s6, v4
	v_mov_b32_e32 v136, 0
	v_mov_b32_e32 v137, 0
	v_mov_b32_e32 v138, 0
	v_mov_b32_e32 v139, 0
	s_and_b64 s[0:1], vcc, s[0:1]
	s_and_saveexec_b64 s[8:9], s[0:1]
	s_cbranch_execz .Lpoolin_5
	global_load_dwordx4 v[136:139], v[226:227], off offset:1024
.Lpoolin_5:
	s_or_b64 exec, exec, s[8:9]
	v_add_co_u32_e32 v226, vcc, 0xc400, v226
	s_nop 1
	v_addc_co_u32_e32 v227, vcc, 0, v227, vcc
	v_add_u32_e32 v4, 48, v7
	v_cmp_le_i32_e32 vcc, s35, v4
	v_cmp_gt_i32_e64 s[0:1], s6, v4
	v_mov_b32_e32 v140, 0
	v_mov_b32_e32 v141, 0
	v_mov_b32_e32 v142, 0
	v_mov_b32_e32 v143, 0
	s_and_b64 s[0:1], vcc, s[0:1]
	s_and_saveexec_b64 s[8:9], s[0:1]
	s_cbranch_execz .Lpoolin_6
	global_load_dwordx4 v[140:143], v[226:227], off offset:1024
.Lpoolin_6:
	s_or_b64 exec, exec, s[8:9]
	v_add_co_u32_e32 v226, vcc, 0xc400, v226
	s_nop 1
	v_addc_co_u32_e32 v227, vcc, 0, v227, vcc
	v_add_u32_e32 v4, 56, v7
	v_cmp_le_i32_e32 vcc, s35, v4
	v_cmp_gt_i32_e64 s[0:1], s6, v4
	v_mov_b32_e32 v144, 0
	v_mov_b32_e32 v145, 0
	v_mov_b32_e32 v146, 0
	v_mov_b32_e32 v147, 0
	s_and_b64 s[0:1], vcc, s[0:1]
	s_and_saveexec_b64 s[8:9], s[0:1]
	s_cbranch_execz .Lpoolin_7
	global_load_dwordx4 v[144:147], v[226:227], off offset:1024
.Lpoolin_7:
	s_or_b64 exec, exec, s[8:9]
	v_add_co_u32_e32 v226, vcc, 0xc400, v226
	s_nop 1
	v_addc_co_u32_e32 v227, vcc, 0, v227, vcc
	v_add_u32_e32 v4, 64, v7
	v_cmp_le_i32_e32 vcc, s35, v4
	v_cmp_gt_i32_e64 s[0:1], s6, v4
	v_mov_b32_e32 v148, 0
	v_mov_b32_e32 v149, 0
	v_mov_b32_e32 v150, 0
	v_mov_b32_e32 v151, 0
	s_and_b64 s[0:1], vcc, s[0:1]
	s_and_saveexec_b64 s[8:9], s[0:1]
	s_cbranch_execz .Lpoolin_8
	global_load_dwordx4 v[148:151], v[226:227], off offset:1024
.Lpoolin_8:
	s_or_b64 exec, exec, s[8:9]
	v_add_co_u32_e32 v226, vcc, 0xc400, v226
	s_nop 1
	v_addc_co_u32_e32 v227, vcc, 0, v227, vcc
	v_add_u32_e32 v4, 72, v7
	v_cmp_le_i32_e32 vcc, s35, v4
	v_cmp_gt_i32_e64 s[0:1], s6, v4
	v_mov_b32_e32 v152, 0
	v_mov_b32_e32 v153, 0
	v_mov_b32_e32 v154, 0
	v_mov_b32_e32 v155, 0
	s_and_b64 s[0:1], vcc, s[0:1]
	s_and_saveexec_b64 s[8:9], s[0:1]
	s_cbranch_execz .Lpoolin_9
	global_load_dwordx4 v[152:155], v[226:227], off offset:1024
.Lpoolin_9:
	s_or_b64 exec, exec, s[8:9]
	s_waitcnt vmcnt(0)
	ds_write_b128 v10, v[116:119]
	ds_write_b128 v10, v[120:123] offset:1152
	ds_write_b128 v10, v[124:127] offset:2304
	ds_write_b128 v10, v[128:131] offset:3456
	ds_write_b128 v10, v[132:135] offset:4608
	ds_write_b128 v10, v[136:139] offset:5760
	ds_write_b128 v10, v[140:143] offset:6912
	ds_write_b128 v10, v[144:147] offset:8064
	ds_write_b128 v10, v[148:151] offset:9216
	ds_write_b128 v10, v[152:155] offset:10368
	v_and_b32_e32 v101, 63, v100
	v_lshrrev_b32_e32 v103, 5, v101
	v_and_b32_e32 v104, 31, v100
	v_lshlrev_b32_e64 v55, v102, 1
	v_lshlrev_b32_e64 v105, v102, 2
	v_lshlrev_b32_e32 v160, 4, v103
	v_mov_b32_e32 v3, 0
	v_mul_u32_u24_e32 v9, 0x90, v104
	v_cmp_lt_i32_e64 s[38:39], 0, v105
	v_mul_lo_u32 v106, v55, s94
	v_add3_u32 v107, v8, v9, v160
	v_mov_b32_e32 v2, v3
	v_mov_b32_e32 v5, v3
	v_mov_b32_e32 v4, v3
	v_mov_b32_e32 v7, v3
	v_mov_b32_e32 v6, v3
	v_mov_b32_e32 v1, v3
	v_mov_b32_e32 v0, v3
	s_waitcnt lgkmcnt(0)
	s_barrier
	s_and_saveexec_b64 s[0:1], s[38:39]
	s_cbranch_execz .LBB0_143
	v_sub_u32_e32 v0, v107, v106
	v_readlane_b32 s2, v246, 33
	s_mov_b64 s[8:9], 0
	v_mov_b32_e32 v10, v105
	v_add_u32_e32 v8, s2, v0
	v_mov_b32_e32 v0, 0
	v_mov_b32_e32 v1, v0
	v_mov_b32_e32 v6, v0
	v_mov_b32_e32 v7, v0
	v_mov_b32_e32 v4, v0
	v_mov_b32_e32 v5, v0
	v_mov_b32_e32 v2, v0
	v_mov_b32_e32 v3, v0

; DI bf16_t f2bf(float x) { return (bf16_t)(pk2(x, 0.f) & 0xffffu); }
; DI void unpack8(u32x4 v, float* x) { x[0] = bflo(v.x); x[1] = bfhi(v.x); x[2] = bflo(v.y); x[3] = bfhi(v.y); x[4] = bflo(v.z); x[5] = bfhi(v.z); x[6] = bflo(v.w); x[7] = bfhi(v.w); }
; DI void sgu_task(const Params& p, int layer, int chunk, int h, unsigned char* lds) {
;   int tid = threadIdx.x; asm volatile("" : "+v"(tid)); const int wid = tid >> 6, lane = tid & 63, r = lane & 31, hh = lane >> 5;
;   const int t0 = chunk * 128;
;   bf16_t* proj = (bf16_t*)(p.ws + WS_PROJ);
;   bf16_t* vT = (bf16_t*)lds;
;   {
;     const int j = tid >> 1, half = tid & 1;
;     const bf16_t* src = proj + (size_t)(t0 + j) * PP + A_V + 64 * h + half * 32;
;     float x[32];
; #pragma unroll
;     for (int i = 0; i < 4; ++i) unpack8(*(const u32x4*)(src + 8 * i), x + 8 * i);
;     float ss = 0.f;
; #pragma unroll
;     for (int e = 0; e < 32; ++e) ss += x[e] * x[e];
;     ss += __shfl_xor(ss, 1);
;     const float rn = rsqrtf(ss * (1.f / 64.f) + EPSF);
; #pragma unroll
;     for (int e = 0; e < 32; ++e) vT[(half * 32 + e) * 136 + j] = f2bf(x[e] * rn);
.LBB0_174:
	s_and_b64 vcc, exec, s[0:1]
	s_cbranch_vccz .LBB0_178
	s_lshl_b32 s1, s4, 5
	v_mov_b32_e32 v35, v180
	s_and_b32 s9, s1, 0x3ff80
	s_add_i32 s8, s9, 0xfffe2000
	v_ashrrev_i32_e32 v0, 1, v35
	v_add_u32_e32 v2, s8, v0
	v_mov_b64_e32 v[0:1], s[46:47]
	s_and_b32 s0, s4, 3
	v_mad_i64_i32 v[0:1], s[6:7], v2, s12, v[0:1]
	v_lshlrev_b32_e32 v2, 5, v35
	s_lshl_b32 s84, s0, 7
	v_and_b32_e32 v30, 32, v2
	v_lshl_add_u64 v[0:1], v[0:1], 0, s[84:85]
	v_lshlrev_b32_e32 v160, 1, v30
	v_lshl_add_u64 v[8:9], v[0:1], 0, v[160:161]
	global_load_dwordx4 v[36:39], v[8:9], off offset:560
	global_load_dwordx4 v[0:3], v[8:9], off offset:544
	global_load_dwordx4 v[4:7], v[8:9], off offset:528
	s_nop 0
	global_load_dwordx4 v[8:11], v[8:9], off offset:512
	v_cmp_lt_i32_e32 vcc, v185, v187
	v_ashrrev_i32_e32 v33, 6, v35
	v_mul_u32_u24_e32 v30, 0x110, v30
	v_and_b32_e32 v32, 31, v35
	v_readlane_b32 s2, v247, 24
	v_readlane_b32 s3, v247, 25
	s_waitcnt vmcnt(2) lgkmcnt(0)
	v_lshlrev_b32_e32 v15, 16, v0
	s_waitcnt vmcnt(1)
	v_lshlrev_b32_e32 v23, 16, v4
	s_waitcnt vmcnt(0)
	v_and_b32_e32 v31, 0xffff0000, v8
	v_lshlrev_b32_e32 v34, 16, v8
	v_lshlrev_b32_e32 v27, 16, v10
	v_and_b32_e32 v26, 0xffff0000, v10
	v_lshlrev_b32_e32 v25, 16, v11
	v_and_b32_e32 v24, 0xffff0000, v11
	v_lshlrev_b32_e32 v11, 16, v2
	v_and_b32_e32 v10, 0xffff0000, v2
	v_mul_f32_e32 v2, v31, v31
	v_lshlrev_b32_e32 v29, 16, v9
	v_fmac_f32_e32 v2, v34, v34
	v_and_b32_e32 v28, 0xffff0000, v9
	v_fmac_f32_e32 v2, v29, v29
	v_fmac_f32_e32 v2, v28, v28
	v_fmac_f32_e32 v2, v27, v27
	v_fmac_f32_e32 v2, v26, v26
	v_fmac_f32_e32 v2, v25, v25
	v_fmac_f32_e32 v2, v24, v24
	v_and_b32_e32 v22, 0xffff0000, v4
	v_fmac_f32_e32 v2, v23, v23
	v_lshlrev_b32_e32 v21, 16, v5
	v_fmac_f32_e32 v2, v22, v22
	v_and_b32_e32 v20, 0xffff0000, v5
	v_fmac_f32_e32 v2, v21, v21
	v_lshlrev_b32_e32 v19, 16, v6
	v_fmac_f32_e32 v2, v20, v20
	v_and_b32_e32 v18, 0xffff0000, v6
	v_fmac_f32_e32 v2, v19, v19
	v_lshlrev_b32_e32 v17, 16, v7
	v_fmac_f32_e32 v2, v18, v18
	v_and_b32_e32 v16, 0xffff0000, v7
	v_fmac_f32_e32 v2, v17, v17
	v_fmac_f32_e32 v2, v16, v16
	v_and_b32_e32 v14, 0xffff0000, v0
	v_fmac_f32_e32 v2, v15, v15
	v_lshlrev_b32_e32 v13, 16, v1
	v_fmac_f32_e32 v2, v14, v14
	v_and_b32_e32 v12, 0xffff0000, v1
	v_fmac_f32_e32 v2, v13, v13
	v_fmac_f32_e32 v2, v12, v12
	v_fmac_f32_e32 v2, v11, v11
	v_and_b32_e32 v8, 0xffff0000, v3
	v_lshlrev_b32_e32 v9, 16, v3
	v_fmac_f32_e32 v2, v10, v10
	v_pk_mul_f32 v[0:1], v[8:9], v[8:9]
	v_and_b32_e32 v6, 0xffff0000, v36
	v_add_f32_e32 v1, v1, v2
	v_lshlrev_b32_e32 v7, 16, v36
	v_add_f32_e32 v2, v0, v1
	v_pk_mul_f32 v[0:1], v[6:7], v[6:7]
	v_and_b32_e32 v4, 0xffff0000, v37
	v_add_f32_e32 v1, v1, v2
	v_lshlrev_b32_e32 v5, 16, v37
	v_add_f32_e32 v2, v0, v1
	v_pk_mul_f32 v[0:1], v[4:5], v[4:5]
	v_lshlrev_b32_e32 v3, 16, v38
	v_add_f32_e32 v1, v1, v2
	v_and_b32_e32 v2, 0xffff0000, v38
	v_add_f32_e32 v36, v0, v1
	v_pk_mul_f32 v[0:1], v[2:3], v[2:3]
	s_nop 0
	v_add_f32_e32 v1, v1, v36
	v_add_f32_e32 v38, v0, v1
	v_and_b32_e32 v0, 0xffff0000, v39
	v_lshlrev_b32_e32 v1, 16, v39
	v_pk_mul_f32 v[36:37], v[0:1], v[0:1]
	s_nop 0
	v_add_f32_e32 v37, v37, v38
	v_add_f32_e32 v36, v36, v37
	v_cndmask_b32_e32 v37, v184, v185, vcc
	v_lshlrev_b32_e32 v37, 2, v37
	ds_bpermute_b32 v37, v37, v36
	s_waitcnt lgkmcnt(0)
	v_add_f32_e32 v36, v36, v37
	v_fmamk_f32 v36, v36, 0x3c800000, v181
	v_cmp_gt_f32_e32 vcc, s44, v36
	v_mul_f32_e32 v37, 0x4b800000, v36
	s_nop 0
	v_cndmask_b32_e32 v36, v36, v37, vcc
	v_rsq_f32_e32 v36, v36
	s_nop 0
	v_mul_f32_e32 v37, 0x45800000, v36
	v_cndmask_b32_e32 v36, v36, v37, vcc
	v_mul_f32_e32 v34, v36, v34
	v_mul_f32_e32 v31, v36, v31
	v_mul_f32_e32 v29, v36, v29
	v_mul_f32_e32 v28, v36, v28
	v_mul_f32_e32 v27, v36, v27
	v_mul_f32_e32 v26, v36, v26
	v_mul_f32_e32 v25, v36, v25
	v_mul_f32_e32 v24, v36, v24
	v_mul_f32_e32 v23, v36, v23
	v_mul_f32_e32 v22, v36, v22
	v_mul_f32_e32 v21, v36, v21
	v_mul_f32_e32 v20, v36, v20
	v_mul_f32_e32 v19, v36, v19
	v_mul_f32_e32 v18, v36, v18
	v_mul_f32_e32 v17, v36, v17
	v_mul_f32_e32 v16, v36, v16
	v_mul_f32_e32 v15, v36, v15
	v_mul_f32_e32 v14, v36, v14
	v_mul_f32_e32 v13, v36, v13
	v_mul_f32_e32 v12, v36, v12
	v_mul_f32_e32 v11, v36, v11
	v_mul_f32_e32 v10, v36, v10
	v_mul_f32_e32 v9, v36, v9
	v_mul_f32_e32 v8, v36, v8
	v_mul_f32_e32 v7, v36, v7
	v_mul_f32_e32 v6, v36, v6
	v_mul_f32_e32 v5, v36, v5
	v_mul_f32_e32 v4, v36, v4
	v_mul_f32_e32 v3, v36, v3
	v_mul_f32_e32 v2, v36, v2
	v_mul_f32_e32 v1, v36, v1
	v_mul_f32_e32 v0, v36, v0
	v_cvt_pk_bf16_f32 v34, v34, s0
	v_cvt_pk_bf16_f32 v31, v31, s0
	v_cvt_pk_bf16_f32 v29, v29, s0
	v_cvt_pk_bf16_f32 v28, v28, s0
	v_cvt_pk_bf16_f32 v27, v27, s0
	v_cvt_pk_bf16_f32 v26, v26, s0
	v_cvt_pk_bf16_f32 v25, v25, s0
	v_cvt_pk_bf16_f32 v24, v24, s0
	v_cvt_pk_bf16_f32 v23, v23, s0
	v_cvt_pk_bf16_f32 v22, v22, s0
	v_cvt_pk_bf16_f32 v21, v21, s0
	v_cvt_pk_bf16_f32 v20, v20, s0
	v_cvt_pk_bf16_f32 v19, v19, s0
	v_cvt_pk_bf16_f32 v18, v18, s0
	v_cvt_pk_bf16_f32 v17, v17, s0
	v_cvt_pk_bf16_f32 v16, v16, s0
	v_cvt_pk_bf16_f32 v15, v15, s0
	v_cvt_pk_bf16_f32 v14, v14, s0
	v_cvt_pk_bf16_f32 v13, v13, s0
	v_cvt_pk_bf16_f32 v12, v12, s0
	v_cvt_pk_bf16_f32 v11, v11, s0
	v_cvt_pk_bf16_f32 v10, v10, s0
	v_cvt_pk_bf16_f32 v9, v9, s0
	v_cvt_pk_bf16_f32 v8, v8, s0
	v_cvt_pk_bf16_f32 v7, v7, s0
	v_cvt_pk_bf16_f32 v6, v6, s0
	v_cvt_pk_bf16_f32 v5, v5, s0
	v_cvt_pk_bf16_f32 v4, v4, s0
	v_cvt_pk_bf16_f32 v3, v3, s0
	v_cvt_pk_bf16_f32 v2, v2, s0
	v_cvt_pk_bf16_f32 v1, v1, s0
	v_cvt_pk_bf16_f32 v0, v0, s0
	s_or_b32 s0, s0, s29
	v_and_b32_e32 v37, -2, v35
	s_ashr_i32 s1, s0, 31
	v_lshlrev_b32_e32 v36, 5, v33
	v_add3_u32 v30, 0, v37, v30
; DI bf16_t f2bf(float x) { return (bf16_t)(pk2(x, 0.f) & 0xffffu); }
; DI int crow(int i, int h) { return (i & 3) + 8 * (i >> 2) + 4 * h; }
; DI f32x16 mfma32(bf16x8 a, bf16x8 b, f32x16 c) { return __builtin_amdgcn_mfma_f32_32x32x16_bf16(a, b, c, 0, 0, 0); }
; DI void sgu_task(const Params& p, int layer, int chunk, int h, unsigned char* lds) {
;     ...
;     for (int e = 0; e < 32; ++e) vT[(half * 32 + e) * 136 + j] = f2bf(x[e] * rn);
;   }
;   __syncthreads();
;   const bf16_t* W = (const bf16_t*)(p.ws + WS_SGUW) + ((size_t)(layer * 4 + h) * 128 + 32 * wid + r) * 128;
;   f32x16 acc[2];
; #pragma unroll
;   for (int a = 0; a < 2; ++a)
; #pragma unroll
;     for (int i = 0; i < 16; ++i) acc[a][i] = 0.f;
; #pragma unroll
;   for (int ks = 0; ks < 8; ++ks) {
;     const bf16x8 a = *(const bf16x8*)(W + 16 * ks + 8 * hh);
; #pragma unroll
;     for (int nt = 0; nt < 2; ++nt) { const bf16x8 b = *(const bf16x8*)(vT + (32 * nt + r) * 136 + 16 * ks + 8 * hh); acc[nt] = mfma32(a, b, acc[nt]); }
;   }
;   const float* bias = p.sgu_b + (layer * 4 + h) * 128;
;   __syncthreads();
;   {
;     float* Ct = (float*)lds + wid * (32 * 68);
; #pragma unroll
;     for (int nt = 0; nt < 2; ++nt)
; #pragma unroll
;       for (int i = 0; i < 16; ++i) Ct[crow(i, hh) * 68 + 32 * nt + r] = acc[nt][i] + bias[32 * wid + crow(i, hh)];
	s_lshl_b64 s[6:7], s[0:1], 7
	v_ashrrev_i32_e32 v37, 31, v36
	ds_write_b16 v30, v1 offset:8160
	ds_write_b16 v30, v0 offset:8432
	v_lshl_add_u64 v[0:1], s[6:7], 0, v[36:37]
	v_or_b32_e32 v0, v0, v32
	ds_write_b16 v30, v34
	v_lshlrev_b64 v[0:1], 8, v[0:1]
	v_bfe_u32 v34, v35, 5, 1
	v_lshl_add_u64 v[0:1], s[2:3], 0, v[0:1]
	v_lshlrev_b32_e32 v160, 4, v34
	v_lshl_add_u64 v[46:47], v[0:1], 0, v[160:161]
	global_load_dwordx4 v[52:55], v[46:47], off
	global_load_dwordx4 v[56:59], v[46:47], off offset:32
	global_load_dwordx4 v[60:63], v[46:47], off offset:64
	global_load_dwordx4 v[64:67], v[46:47], off offset:96
	global_load_dwordx4 v[68:71], v[46:47], off offset:128
	global_load_dwordx4 v[72:75], v[46:47], off offset:160
	global_load_dwordx4 v[76:79], v[46:47], off offset:192
	global_load_dwordx4 v[80:83], v[46:47], off offset:224
	ds_write_b16 v30, v31 offset:272
	ds_write_b16 v30, v29 offset:544
	ds_write_b16 v30, v28 offset:816
	ds_write_b16 v30, v27 offset:1088
	ds_write_b16 v30, v26 offset:1360
	ds_write_b16 v30, v25 offset:1632
	ds_write_b16 v30, v24 offset:1904
	ds_write_b16 v30, v23 offset:2176
	ds_write_b16 v30, v22 offset:2448
	ds_write_b16 v30, v21 offset:2720
	ds_write_b16 v30, v20 offset:2992
	ds_write_b16 v30, v19 offset:3264
	ds_write_b16 v30, v18 offset:3536
	ds_write_b16 v30, v17 offset:3808
	ds_write_b16 v30, v16 offset:4080
	ds_write_b16 v30, v15 offset:4352
	ds_write_b16 v30, v14 offset:4624
	ds_write_b16 v30, v13 offset:4896
	ds_write_b16 v30, v12 offset:5168
	ds_write_b16 v30, v11 offset:5440
	ds_write_b16 v30, v10 offset:5712
	ds_write_b16 v30, v9 offset:5984
	ds_write_b16 v30, v8 offset:6256
	ds_write_b16 v30, v7 offset:6528
	ds_write_b16 v30, v6 offset:6800
	ds_write_b16 v30, v5 offset:7072
	ds_write_b16 v30, v4 offset:7344
	ds_write_b16 v30, v3 offset:7616
	ds_write_b16 v30, v2 offset:7888
	s_waitcnt lgkmcnt(0)
	s_barrier
	v_mul_u32_u24_e32 v4, 0x110, v32
	v_add3_u32 v48, 0, v160, v4
	ds_read_b128 v[4:7], v48
	ds_read_b128 v[38:41], v48 offset:32
	s_waitcnt vmcnt(7) lgkmcnt(1)
	v_mfma_f32_32x32x16_bf16 v[16:31], v[52:55], v[4:7], 0
	ds_read_b128 v[4:7], v48 offset:8704
	s_lshl_b32 s0, s0, 7
	s_ashr_i32 s1, s0, 31
	s_movk_i32 s2, 0x2200
	s_lshl_b64 s[0:1], s[0:1], 2
	v_lshlrev_b32_e32 v32, 2, v32
	s_add_u32 s0, s58, s0
	s_waitcnt vmcnt(6) lgkmcnt(1)
	v_mfma_f32_32x32x16_bf16 v[16:31], v[56:59], v[38:41], v[16:31]
	ds_read_b128 v[38:41], v48 offset:8736
	s_addc_u32 s1, s59, s1
	s_waitcnt lgkmcnt(1)
	v_mfma_f32_32x32x16_bf16 v[0:15], v[52:55], v[4:7], 0
	s_waitcnt lgkmcnt(0)
	v_mfma_f32_32x32x16_bf16 v[0:15], v[56:59], v[38:41], v[0:15]
	ds_read_b128 v[42:45], v48 offset:64
	s_waitcnt vmcnt(5) lgkmcnt(0)
	v_mfma_f32_32x32x16_bf16 v[16:31], v[60:63], v[42:45], v[16:31]
	ds_read_b128 v[42:45], v48 offset:8768
	s_waitcnt lgkmcnt(0)
	v_mfma_f32_32x32x16_bf16 v[0:15], v[60:63], v[42:45], v[0:15]
	ds_read_b128 v[42:45], v48 offset:96
	s_waitcnt vmcnt(4) lgkmcnt(0)
	v_mfma_f32_32x32x16_bf16 v[16:31], v[64:67], v[42:45], v[16:31]
	ds_read_b128 v[42:45], v48 offset:8800
	s_waitcnt lgkmcnt(0)
	v_mfma_f32_32x32x16_bf16 v[0:15], v[64:67], v[42:45], v[0:15]
	ds_read_b128 v[42:45], v48 offset:128
	s_waitcnt vmcnt(3) lgkmcnt(0)
	v_mfma_f32_32x32x16_bf16 v[16:31], v[68:71], v[42:45], v[16:31]
	ds_read_b128 v[42:45], v48 offset:8832
	s_waitcnt lgkmcnt(0)
	v_mfma_f32_32x32x16_bf16 v[0:15], v[68:71], v[42:45], v[0:15]
	ds_read_b128 v[42:45], v48 offset:160
	s_waitcnt vmcnt(2) lgkmcnt(0)
	v_mfma_f32_32x32x16_bf16 v[16:31], v[72:75], v[42:45], v[16:31]
	ds_read_b128 v[42:45], v48 offset:8864
	s_waitcnt lgkmcnt(0)
	v_mfma_f32_32x32x16_bf16 v[0:15], v[72:75], v[42:45], v[0:15]
	ds_read_b128 v[42:45], v48 offset:192
	s_waitcnt vmcnt(1) lgkmcnt(0)
	v_mfma_f32_32x32x16_bf16 v[16:31], v[76:79], v[42:45], v[16:31]
	ds_read_b128 v[42:45], v48 offset:8896
	s_waitcnt lgkmcnt(0)
	v_mfma_f32_32x32x16_bf16 v[0:15], v[76:79], v[42:45], v[0:15]
	ds_read_b128 v[42:45], v48 offset:224
	s_waitcnt vmcnt(0) lgkmcnt(0)
	v_mfma_f32_32x32x16_bf16 v[16:31], v[80:83], v[42:45], v[16:31]
	ds_read_b128 v[42:45], v48 offset:8928
	s_waitcnt lgkmcnt(0)
	s_barrier
	v_mfma_f32_32x32x16_bf16 v[0:15], v[80:83], v[42:45], v[0:15]
	v_mul_lo_u32 v40, v33, s2
	v_lshlrev_b32_e32 v41, 2, v34
	v_add3_u32 v42, 0, v40, v32
	v_or_b32_e32 v32, v41, v36
	v_ashrrev_i32_e32 v33, 31, v32
	v_lshl_add_u64 v[38:39], v[32:33], 2, s[0:1]
	v_mov_b32_e32 v33, v37
	s_movk_i32 s2, 0x440
	v_lshl_add_u64 v[38:39], v[32:33], 2, s[0:1]
	v_mad_u32_u24 v44, v34, s2, v42
	global_load_dwordx4 v[88:91], v[38:39], off
	global_load_dwordx4 v[92:95], v[38:39], off offset:32
	global_load_dwordx4 v[96:99], v[38:39], off offset:64
	global_load_dwordx4 v[132:135], v[38:39], off offset:96
	s_movk_i32 s2, 0x110
	s_waitcnt vmcnt(0)
	v_add_f32_e32 v16, v16, v88
	ds_write_b32 v44, v16
	v_or_b32_e32 v16, 1, v41
	v_mad_u32_u24 v37, v16, s2, v42
	v_add_f32_e32 v0, v0, v88
	s_waitcnt vmcnt(0)
	v_add_f32_e32 v16, v18, v90
	v_add_f32_e32 v17, v17, v89
	ds_write_b32 v37, v16 offset:272
	v_add_f32_e32 v16, v19, v91
	ds_write_b32 v37, v17
	ds_write_b32 v37, v16 offset:544
	s_waitcnt vmcnt(0)
	v_add_f32_e32 v20, v20, v92
	ds_write_b32 v37, v20 offset:1904
	v_add_f32_e32 v20, v21, v93
	ds_write_b32 v37, v20 offset:2176
	v_add_f32_e32 v20, v22, v94
	ds_write_b32 v37, v20 offset:2448
	v_add_f32_e32 v20, v23, v95
	ds_write_b32 v37, v20 offset:2720
	s_waitcnt vmcnt(0)
	v_add_f32_e32 v24, v24, v96
	ds_write_b32 v37, v24 offset:4080
	v_add_f32_e32 v24, v25, v97
	ds_write_b32 v37, v24 offset:4352
	v_add_f32_e32 v24, v26, v98
	ds_write_b32 v37, v24 offset:4624
	v_add_f32_e32 v24, v27, v99
	ds_write_b32 v37, v24 offset:4896
	s_waitcnt vmcnt(0)
; DI float bflo(unsigned u) { return __uint_as_float(u << 16); }
; DI float bfhi(unsigned u) { return __uint_as_float(u & 0xffff0000u); }
; DI unsigned pk2(float lo, float hi) { f32x2 v = {lo, hi}; bfv2 b = __builtin_convertvector(v, bfv2); return __builtin_bit_cast(unsigned, b); }
; DI float silu(float x) { return x * __builtin_amdgcn_rcpf(1.f + __expf(-x)); }
; DI int crow(int i, int h) { return (i & 3) + 8 * (i >> 2) + 4 * h; }
; DI void sgu_task(const Params& p, int layer, int chunk, int h, unsigned char* lds) {
;     ...
;       for (int i = 0; i < 16; ++i) Ct[crow(i, hh) * 68 + 32 * nt + r] = acc[nt][i] + bias[32 * wid + crow(i, hh)];
;     asm volatile("s_waitcnt lgkmcnt(0)" ::: "memory");
;     const int rsub = lane >> 4, c4 = (lane & 15) * 4;
; #pragma unroll 4
;     for (int j = 0; j < 8; ++j) {
;       const int rl = 4 * j + rsub;
;       const f32x4 cv = *(const f32x4*)(Ct + rl * 68 + c4);
;       bf16_t* base = proj + (size_t)(t0 + 32 * wid + rl) * PP + 64 * h + c4;
;       const u32x2 ur = *(const u32x2*)(base + A_U), zr = *(const u32x2*)(base + A_Z);
;       *(u32x2*)(base + A_U) = (u32x2){pk2(bflo(ur.x) * cv.x * silu(bflo(zr.x)), bfhi(ur.x) * cv.y * silu(bfhi(zr.x))), pk2(bflo(ur.y) * cv.z * silu(bflo(zr.y)), bfhi(ur.y) * cv.w * silu(bfhi(zr.y)))};
;     }
	v_add_f32_e32 v28, v28, v132
	ds_write_b32 v37, v28 offset:6256
	v_add_f32_e32 v28, v29, v133
	ds_write_b32 v37, v28 offset:6528
	v_add_f32_e32 v28, v30, v134
	ds_write_b32 v37, v28 offset:6800
	v_add_f32_e32 v28, v31, v135
	ds_write_b32 v37, v28 offset:7072
	ds_write_b32 v44, v0 offset:128
	v_add_f32_e32 v0, v1, v89
	ds_write_b32 v37, v0 offset:128
	v_add_f32_e32 v0, v2, v90
	ds_write_b32 v37, v0 offset:400
	v_add_f32_e32 v0, v3, v91
	ds_write_b32 v37, v0 offset:672
	v_add_f32_e32 v0, v4, v92
	ds_write_b32 v37, v0 offset:2032
	v_add_f32_e32 v0, v5, v93
	ds_write_b32 v37, v0 offset:2304
	v_add_f32_e32 v0, v6, v94
	ds_write_b32 v37, v0 offset:2576
	v_add_f32_e32 v0, v7, v95
	ds_write_b32 v37, v0 offset:2848
	v_add_f32_e32 v0, v8, v96
	ds_write_b32 v37, v0 offset:4208
	v_add_f32_e32 v0, v9, v97
	ds_write_b32 v37, v0 offset:4480
	v_add_f32_e32 v0, v10, v98
	ds_write_b32 v37, v0 offset:4752
	v_add_f32_e32 v0, v11, v99
	ds_write_b32 v37, v0 offset:5024
	v_add_f32_e32 v0, v12, v132
	ds_write_b32 v37, v0 offset:6384
	v_add_f32_e32 v0, v13, v133
	ds_write_b32 v37, v0 offset:6656
	v_add_f32_e32 v0, v14, v134
	ds_write_b32 v37, v0 offset:6928
	v_add_f32_e32 v0, v15, v135
	v_bfe_u32 v10, v35, 4, 2
	ds_write_b32 v37, v0 offset:7200
	v_or_b32_e32 v0, s9, v10
	v_add_u32_e32 v8, v0, v36
	v_add_u32_e32 v2, 0xfffe200c, v8
	v_mov_b64_e32 v[0:1], s[84:85]
	v_and_b32_e32 v6, 15, v35
	v_mad_i64_i32 v[2:3], s[0:1], v2, s12, v[0:1]
	v_lshlrev_b32_e32 v11, 3, v6
	v_or_b32_e32 v2, v2, v11
	v_lshl_add_u64 v[4:5], s[88:89], 0, v[2:3]
	v_mad_u32_u24 v2, v10, s2, v40
	v_lshlrev_b32_e32 v3, 4, v6
	v_add3_u32 v12, v2, v3, 0
	v_add_u32_e32 v2, 0xfffe2008, v8
	v_mad_i64_i32 v[2:3], s[0:1], v2, s12, v[0:1]
	v_or_b32_e32 v2, v2, v11
	v_lshl_add_u64 v[6:7], s[88:89], 0, v[2:3]
	v_add_u32_e32 v2, 0xfffe2004, v8
	v_mad_i64_i32 v[2:3], s[0:1], v2, s12, v[0:1]
	v_or_b32_e32 v2, v2, v11
	v_lshl_add_u64 v[8:9], s[88:89], 0, v[2:3]
	v_or_b32_e32 v2, s8, v10
	s_waitcnt lgkmcnt(0)
	v_add_u32_e32 v2, v2, v36
	v_mad_i64_i32 v[0:1], s[0:1], v2, s12, v[0:1]
	v_or_b32_e32 v0, v0, v11
	v_lshl_add_u64 v[10:11], s[88:89], 0, v[0:1]
	s_mov_b64 s[0:1], 0
	v_add_co_u32_e32 v226, vcc, 0x1438000, v10
	s_nop 1
	v_addc_co_u32_e32 v227, vcc, 0, v11, vcc
	global_load_dwordx2 v[100:101], v[226:227], off offset:256
	global_load_dwordx2 v[102:103], v[226:227], off offset:1280
	v_add_co_u32_e32 v226, vcc, 0x1438000, v8
	s_nop 1
	v_addc_co_u32_e32 v227, vcc, 0, v9, vcc
	global_load_dwordx2 v[104:105], v[226:227], off offset:256
	global_load_dwordx2 v[106:107], v[226:227], off offset:1280
	v_add_co_u32_e32 v226, vcc, 0x1438000, v6
	s_nop 1
	v_addc_co_u32_e32 v227, vcc, 0, v7, vcc
	global_load_dwordx2 v[108:109], v[226:227], off offset:256
	global_load_dwordx2 v[110:111], v[226:227], off offset:1280
	v_add_co_u32_e32 v226, vcc, 0x1438000, v4
	s_nop 1
	v_addc_co_u32_e32 v227, vcc, 0, v5, vcc
	global_load_dwordx2 v[112:113], v[226:227], off offset:256
	global_load_dwordx2 v[114:115], v[226:227], off offset:1280
	v_add_co_u32_e32 v226, vcc, 0x1450800, v10
	s_nop 1
	v_addc_co_u32_e32 v227, vcc, 0, v11, vcc
	global_load_dwordx2 v[116:117], v[226:227], off offset:256
	global_load_dwordx2 v[118:119], v[226:227], off offset:1280
	v_add_co_u32_e32 v226, vcc, 0x1450800, v8
	s_nop 1
	v_addc_co_u32_e32 v227, vcc, 0, v9, vcc
	global_load_dwordx2 v[120:121], v[226:227], off offset:256
	global_load_dwordx2 v[122:123], v[226:227], off offset:1280
	v_add_co_u32_e32 v226, vcc, 0x1450800, v6
	s_nop 1
	v_addc_co_u32_e32 v227, vcc, 0, v7, vcc
	global_load_dwordx2 v[124:125], v[226:227], off offset:256
	global_load_dwordx2 v[126:127], v[226:227], off offset:1280
	v_add_co_u32_e32 v226, vcc, 0x1450800, v4
	s_nop 1
	v_addc_co_u32_e32 v227, vcc, 0, v5, vcc
	global_load_dwordx2 v[128:129], v[226:227], off offset:256
	global_load_dwordx2 v[130:131], v[226:227], off offset:1280
	v_lshl_add_u64 v[14:15], v[10:11], 0, s[0:1]
	v_add_co_u32_e32 v14, vcc, 0x1438000, v14
	ds_read_b128 v[0:3], v12
	s_nop 0
	v_addc_co_u32_e32 v15, vcc, 0, v15, vcc
	s_waitcnt vmcnt(15)
	v_mov_b32_e32 v16, v100
	v_mov_b32_e32 v17, v101
	v_lshlrev_b32_e32 v24, 16, v16
	s_waitcnt vmcnt(14)
	v_mov_b32_e32 v18, v102
	v_mov_b32_e32 v19, v103
	v_lshlrev_b32_e32 v20, 16, v18
	v_mul_f32_e32 v13, 0xbfb8aa3b, v20
	v_exp_f32_e32 v13, v13
	v_and_b32_e32 v21, 0xffff0000, v18
	v_and_b32_e32 v25, 0xffff0000, v16
	s_waitcnt lgkmcnt(0)
	v_pk_mul_f32 v[0:1], v[0:1], v[24:25]
	v_add_f32_e32 v13, 1.0, v13
	v_rcp_f32_e32 v22, v13
	v_mul_f32_e32 v13, 0xbfb8aa3b, v21
	v_exp_f32_e32 v13, v13
	v_lshlrev_b32_e32 v18, 16, v19
	v_and_b32_e32 v19, 0xffff0000, v19
	v_add_f32_e32 v13, 1.0, v13
	v_rcp_f32_e32 v23, v13
	s_nop 0
	v_pk_mul_f32 v[20:21], v[22:23], v[20:21]
	s_nop 0
	v_pk_mul_f32 v[0:1], v[0:1], v[20:21]
	v_lshlrev_b32_e32 v20, 16, v17
	v_cvt_pk_bf16_f32 v0, v0, v1
	v_mul_f32_e32 v1, 0xbfb8aa3b, v18
	v_exp_f32_e32 v1, v1
	v_and_b32_e32 v21, 0xffff0000, v17
	v_pk_mul_f32 v[2:3], v[2:3], v[20:21]
	v_add_f32_e32 v1, 1.0, v1
	v_rcp_f32_e32 v16, v1
	v_mul_f32_e32 v1, 0xbfb8aa3b, v19
	v_exp_f32_e32 v1, v1
	s_nop 0
	v_add_f32_e32 v1, 1.0, v1
	v_rcp_f32_e32 v17, v1
	s_nop 0
	v_pk_mul_f32 v[16:17], v[16:17], v[18:19]
	s_nop 0
	v_pk_mul_f32 v[2:3], v[2:3], v[16:17]
	s_nop 0
	v_cvt_pk_bf16_f32 v1, v2, v3
	global_store_dwordx2 v[14:15], v[0:1], off offset:256
	v_lshl_add_u64 v[14:15], v[8:9], 0, s[0:1]
	v_add_co_u32_e32 v14, vcc, s80, v14
	ds_read_b128 v[0:3], v12 offset:1088
	s_nop 0
	v_addc_co_u32_e32 v15, vcc, 0, v15, vcc
	s_waitcnt vmcnt(14)
	v_mov_b32_e32 v16, v104
	v_mov_b32_e32 v17, v105
	v_lshlrev_b32_e32 v24, 16, v16
	s_waitcnt vmcnt(13)
; DI float bflo(unsigned u) { return __uint_as_float(u << 16); }
; DI float bfhi(unsigned u) { return __uint_as_float(u & 0xffff0000u); }
; DI unsigned pk2(float lo, float hi) { f32x2 v = {lo, hi}; bfv2 b = __builtin_convertvector(v, bfv2); return __builtin_bit_cast(unsigned, b); }
; DI float silu(float x) { return x * __builtin_amdgcn_rcpf(1.f + __expf(-x)); }
; DI void sgu_task(const Params& p, int layer, int chunk, int h, unsigned char* lds) {
;     ...
;     for (int j = 0; j < 8; ++j) {
;       const int rl = 4 * j + rsub;
;       const f32x4 cv = *(const f32x4*)(Ct + rl * 68 + c4);
;       bf16_t* base = proj + (size_t)(t0 + 32 * wid + rl) * PP + 64 * h + c4;
;       const u32x2 ur = *(const u32x2*)(base + A_U), zr = *(const u32x2*)(base + A_Z);
;       *(u32x2*)(base + A_U) = (u32x2){pk2(bflo(ur.x) * cv.x * silu(bflo(zr.x)), bfhi(ur.x) * cv.y * silu(bfhi(zr.x))), pk2(bflo(ur.y) * cv.z * silu(bflo(zr.y)), bfhi(ur.y) * cv.w * silu(bfhi(zr.y)))};
;     }
	v_mov_b32_e32 v18, v106
	v_mov_b32_e32 v19, v107
	v_lshlrev_b32_e32 v20, 16, v18
	v_mul_f32_e32 v13, 0xbfb8aa3b, v20
	v_exp_f32_e32 v13, v13
	v_and_b32_e32 v21, 0xffff0000, v18
	v_and_b32_e32 v25, 0xffff0000, v16
	s_waitcnt lgkmcnt(0)
	v_pk_mul_f32 v[0:1], v[0:1], v[24:25]
	v_add_f32_e32 v13, 1.0, v13
	v_rcp_f32_e32 v22, v13
	v_mul_f32_e32 v13, 0xbfb8aa3b, v21
	v_exp_f32_e32 v13, v13
	v_lshlrev_b32_e32 v18, 16, v19
	v_and_b32_e32 v19, 0xffff0000, v19
	v_add_f32_e32 v13, 1.0, v13
	v_rcp_f32_e32 v23, v13
	s_nop 0
	v_pk_mul_f32 v[20:21], v[22:23], v[20:21]
	s_nop 0
	v_pk_mul_f32 v[0:1], v[0:1], v[20:21]
	v_lshlrev_b32_e32 v20, 16, v17
	v_cvt_pk_bf16_f32 v0, v0, v1
	v_mul_f32_e32 v1, 0xbfb8aa3b, v18
	v_exp_f32_e32 v1, v1
	v_and_b32_e32 v21, 0xffff0000, v17
	v_pk_mul_f32 v[2:3], v[2:3], v[20:21]
	v_add_f32_e32 v1, 1.0, v1
	v_rcp_f32_e32 v16, v1
	v_mul_f32_e32 v1, 0xbfb8aa3b, v19
	v_exp_f32_e32 v1, v1
	s_nop 0
	v_add_f32_e32 v1, 1.0, v1
	v_rcp_f32_e32 v17, v1
	s_nop 0
	v_pk_mul_f32 v[16:17], v[16:17], v[18:19]
	s_nop 0
	v_pk_mul_f32 v[2:3], v[2:3], v[16:17]
	s_nop 0
	v_cvt_pk_bf16_f32 v1, v2, v3
	global_store_dwordx2 v[14:15], v[0:1], off offset:256
	v_lshl_add_u64 v[14:15], v[6:7], 0, s[0:1]
	v_add_co_u32_e32 v14, vcc, s80, v14
	ds_read_b128 v[0:3], v12 offset:2176
	s_nop 0
	v_addc_co_u32_e32 v15, vcc, 0, v15, vcc
	s_waitcnt vmcnt(13)
	v_mov_b32_e32 v16, v108
	v_mov_b32_e32 v17, v109
	v_lshlrev_b32_e32 v24, 16, v16
	s_waitcnt vmcnt(12)
	v_mov_b32_e32 v18, v110
	v_mov_b32_e32 v19, v111
	v_lshlrev_b32_e32 v20, 16, v18
	v_mul_f32_e32 v13, 0xbfb8aa3b, v20
	v_exp_f32_e32 v13, v13
	v_and_b32_e32 v21, 0xffff0000, v18
	v_and_b32_e32 v25, 0xffff0000, v16
	s_waitcnt lgkmcnt(0)
	v_pk_mul_f32 v[0:1], v[0:1], v[24:25]
	v_add_f32_e32 v13, 1.0, v13
	v_rcp_f32_e32 v22, v13
	v_mul_f32_e32 v13, 0xbfb8aa3b, v21
	v_exp_f32_e32 v13, v13
	v_lshlrev_b32_e32 v18, 16, v19
	v_and_b32_e32 v19, 0xffff0000, v19
	v_add_f32_e32 v13, 1.0, v13
	v_rcp_f32_e32 v23, v13
	s_nop 0
	v_pk_mul_f32 v[20:21], v[22:23], v[20:21]
	s_nop 0
	v_pk_mul_f32 v[0:1], v[0:1], v[20:21]
	v_lshlrev_b32_e32 v20, 16, v17
	v_cvt_pk_bf16_f32 v0, v0, v1
	v_mul_f32_e32 v1, 0xbfb8aa3b, v18
	v_exp_f32_e32 v1, v1
	v_and_b32_e32 v21, 0xffff0000, v17
	v_pk_mul_f32 v[2:3], v[2:3], v[20:21]
	v_add_f32_e32 v1, 1.0, v1
	v_rcp_f32_e32 v16, v1
	v_mul_f32_e32 v1, 0xbfb8aa3b, v19
	v_exp_f32_e32 v1, v1
	s_nop 0
	v_add_f32_e32 v1, 1.0, v1
	v_rcp_f32_e32 v17, v1
	s_nop 0
	v_pk_mul_f32 v[16:17], v[16:17], v[18:19]
	s_nop 0
	v_pk_mul_f32 v[2:3], v[2:3], v[16:17]
	s_nop 0
	v_cvt_pk_bf16_f32 v1, v2, v3
	global_store_dwordx2 v[14:15], v[0:1], off offset:256
	v_lshl_add_u64 v[14:15], v[4:5], 0, s[0:1]
	v_add_co_u32_e32 v14, vcc, s80, v14
	ds_read_b128 v[0:3], v12 offset:3264
	s_nop 0
	v_addc_co_u32_e32 v15, vcc, 0, v15, vcc
	s_add_u32 s0, s0, 0x18800
	s_addc_u32 s1, s1, 0
	v_add_u32_e32 v12, 0x1100, v12
	s_cmp_lg_u32 s0, 0x31000
	s_waitcnt vmcnt(12)
	v_mov_b32_e32 v16, v112
	v_mov_b32_e32 v17, v113
	v_lshlrev_b32_e32 v24, 16, v16
	s_waitcnt vmcnt(11)
	v_mov_b32_e32 v18, v114
	v_mov_b32_e32 v19, v115
	v_lshlrev_b32_e32 v20, 16, v18
	v_mul_f32_e32 v13, 0xbfb8aa3b, v20
	v_exp_f32_e32 v13, v13
	v_and_b32_e32 v21, 0xffff0000, v18
	v_and_b32_e32 v25, 0xffff0000, v16
	s_waitcnt lgkmcnt(0)
	v_pk_mul_f32 v[0:1], v[0:1], v[24:25]
	v_add_f32_e32 v13, 1.0, v13
	v_rcp_f32_e32 v22, v13
	v_mul_f32_e32 v13, 0xbfb8aa3b, v21
	v_exp_f32_e32 v13, v13
	v_lshlrev_b32_e32 v18, 16, v19
	v_and_b32_e32 v19, 0xffff0000, v19
	v_add_f32_e32 v13, 1.0, v13
	v_rcp_f32_e32 v23, v13
	s_nop 0
	v_pk_mul_f32 v[20:21], v[22:23], v[20:21]
	s_nop 0
	v_pk_mul_f32 v[0:1], v[0:1], v[20:21]
	v_lshlrev_b32_e32 v20, 16, v17
	v_cvt_pk_bf16_f32 v0, v0, v1
	v_mul_f32_e32 v1, 0xbfb8aa3b, v18
	v_exp_f32_e32 v1, v1
	v_and_b32_e32 v21, 0xffff0000, v17
	v_pk_mul_f32 v[2:3], v[2:3], v[20:21]
	v_add_f32_e32 v1, 1.0, v1
	v_rcp_f32_e32 v16, v1
	v_mul_f32_e32 v1, 0xbfb8aa3b, v19
	v_exp_f32_e32 v1, v1
	s_nop 0
	v_add_f32_e32 v1, 1.0, v1
	v_rcp_f32_e32 v17, v1
	s_nop 0
	v_pk_mul_f32 v[16:17], v[16:17], v[18:19]
	s_nop 0
	v_pk_mul_f32 v[2:3], v[2:3], v[16:17]
	s_nop 0
	v_cvt_pk_bf16_f32 v1, v2, v3
	global_store_dwordx2 v[14:15], v[0:1], off offset:256
	v_lshl_add_u64 v[14:15], v[10:11], 0, s[0:1]
	v_add_co_u32_e32 v14, vcc, 0x1438000, v14
	ds_read_b128 v[0:3], v12
	s_nop 0
	v_addc_co_u32_e32 v15, vcc, 0, v15, vcc
	s_waitcnt vmcnt(11)
	v_mov_b32_e32 v16, v116
	v_mov_b32_e32 v17, v117
	v_lshlrev_b32_e32 v24, 16, v16
	s_waitcnt vmcnt(10)
	v_mov_b32_e32 v18, v118
	v_mov_b32_e32 v19, v119
	v_lshlrev_b32_e32 v20, 16, v18
	v_mul_f32_e32 v13, 0xbfb8aa3b, v20
	v_exp_f32_e32 v13, v13
	v_and_b32_e32 v21, 0xffff0000, v18
	v_and_b32_e32 v25, 0xffff0000, v16
	s_waitcnt lgkmcnt(0)
; DI float bflo(unsigned u) { return __uint_as_float(u << 16); }
; DI float bfhi(unsigned u) { return __uint_as_float(u & 0xffff0000u); }
; DI unsigned pk2(float lo, float hi) { f32x2 v = {lo, hi}; bfv2 b = __builtin_convertvector(v, bfv2); return __builtin_bit_cast(unsigned, b); }
; DI float silu(float x) { return x * __builtin_amdgcn_rcpf(1.f + __expf(-x)); }
; DI void sgu_task(const Params& p, int layer, int chunk, int h, unsigned char* lds) {
;     ...
;     for (int j = 0; j < 8; ++j) {
;       const int rl = 4 * j + rsub;
;       const f32x4 cv = *(const f32x4*)(Ct + rl * 68 + c4);
;       bf16_t* base = proj + (size_t)(t0 + 32 * wid + rl) * PP + 64 * h + c4;
;       const u32x2 ur = *(const u32x2*)(base + A_U), zr = *(const u32x2*)(base + A_Z);
;       *(u32x2*)(base + A_U) = (u32x2){pk2(bflo(ur.x) * cv.x * silu(bflo(zr.x)), bfhi(ur.x) * cv.y * silu(bfhi(zr.x))), pk2(bflo(ur.y) * cv.z * silu(bflo(zr.y)), bfhi(ur.y) * cv.w * silu(bfhi(zr.y)))};
;     }
;   }
;   __syncthreads();
	v_pk_mul_f32 v[0:1], v[0:1], v[24:25]
	v_add_f32_e32 v13, 1.0, v13
	v_rcp_f32_e32 v22, v13
	v_mul_f32_e32 v13, 0xbfb8aa3b, v21
	v_exp_f32_e32 v13, v13
	v_lshlrev_b32_e32 v18, 16, v19
	v_and_b32_e32 v19, 0xffff0000, v19
	v_add_f32_e32 v13, 1.0, v13
	v_rcp_f32_e32 v23, v13
	s_nop 0
	v_pk_mul_f32 v[20:21], v[22:23], v[20:21]
	s_nop 0
	v_pk_mul_f32 v[0:1], v[0:1], v[20:21]
	v_lshlrev_b32_e32 v20, 16, v17
	v_cvt_pk_bf16_f32 v0, v0, v1
	v_mul_f32_e32 v1, 0xbfb8aa3b, v18
	v_exp_f32_e32 v1, v1
	v_and_b32_e32 v21, 0xffff0000, v17
	v_pk_mul_f32 v[2:3], v[2:3], v[20:21]
	v_add_f32_e32 v1, 1.0, v1
	v_rcp_f32_e32 v16, v1
	v_mul_f32_e32 v1, 0xbfb8aa3b, v19
	v_exp_f32_e32 v1, v1
	s_nop 0
	v_add_f32_e32 v1, 1.0, v1
	v_rcp_f32_e32 v17, v1
	s_nop 0
	v_pk_mul_f32 v[16:17], v[16:17], v[18:19]
	s_nop 0
	v_pk_mul_f32 v[2:3], v[2:3], v[16:17]
	s_nop 0
	v_cvt_pk_bf16_f32 v1, v2, v3
	global_store_dwordx2 v[14:15], v[0:1], off offset:256
	v_lshl_add_u64 v[14:15], v[8:9], 0, s[0:1]
	v_add_co_u32_e32 v14, vcc, s80, v14
	ds_read_b128 v[0:3], v12 offset:1088
	s_nop 0
	v_addc_co_u32_e32 v15, vcc, 0, v15, vcc
	s_waitcnt vmcnt(10)
	v_mov_b32_e32 v16, v120
	v_mov_b32_e32 v17, v121
	v_lshlrev_b32_e32 v24, 16, v16
	s_waitcnt vmcnt(9)
	v_mov_b32_e32 v18, v122
	v_mov_b32_e32 v19, v123
	v_lshlrev_b32_e32 v20, 16, v18
	v_mul_f32_e32 v13, 0xbfb8aa3b, v20
	v_exp_f32_e32 v13, v13
	v_and_b32_e32 v21, 0xffff0000, v18
	v_and_b32_e32 v25, 0xffff0000, v16
	s_waitcnt lgkmcnt(0)
	v_pk_mul_f32 v[0:1], v[0:1], v[24:25]
	v_add_f32_e32 v13, 1.0, v13
	v_rcp_f32_e32 v22, v13
	v_mul_f32_e32 v13, 0xbfb8aa3b, v21
	v_exp_f32_e32 v13, v13
	v_lshlrev_b32_e32 v18, 16, v19
	v_and_b32_e32 v19, 0xffff0000, v19
	v_add_f32_e32 v13, 1.0, v13
	v_rcp_f32_e32 v23, v13
	s_nop 0
	v_pk_mul_f32 v[20:21], v[22:23], v[20:21]
	s_nop 0
	v_pk_mul_f32 v[0:1], v[0:1], v[20:21]
	v_lshlrev_b32_e32 v20, 16, v17
	v_cvt_pk_bf16_f32 v0, v0, v1
	v_mul_f32_e32 v1, 0xbfb8aa3b, v18
	v_exp_f32_e32 v1, v1
	v_and_b32_e32 v21, 0xffff0000, v17
	v_pk_mul_f32 v[2:3], v[2:3], v[20:21]
	v_add_f32_e32 v1, 1.0, v1
	v_rcp_f32_e32 v16, v1
	v_mul_f32_e32 v1, 0xbfb8aa3b, v19
	v_exp_f32_e32 v1, v1
	s_nop 0
	v_add_f32_e32 v1, 1.0, v1
	v_rcp_f32_e32 v17, v1
	s_nop 0
	v_pk_mul_f32 v[16:17], v[16:17], v[18:19]
	s_nop 0
	v_pk_mul_f32 v[2:3], v[2:3], v[16:17]
	s_nop 0
	v_cvt_pk_bf16_f32 v1, v2, v3
	global_store_dwordx2 v[14:15], v[0:1], off offset:256
	v_lshl_add_u64 v[14:15], v[6:7], 0, s[0:1]
	v_add_co_u32_e32 v14, vcc, s80, v14
	ds_read_b128 v[0:3], v12 offset:2176
	s_nop 0
	v_addc_co_u32_e32 v15, vcc, 0, v15, vcc
	s_waitcnt vmcnt(9)
	v_mov_b32_e32 v16, v124
	v_mov_b32_e32 v17, v125
	v_lshlrev_b32_e32 v24, 16, v16
	s_waitcnt vmcnt(8)
	v_mov_b32_e32 v18, v126
	v_mov_b32_e32 v19, v127
	v_lshlrev_b32_e32 v20, 16, v18
	v_mul_f32_e32 v13, 0xbfb8aa3b, v20
	v_exp_f32_e32 v13, v13
	v_and_b32_e32 v21, 0xffff0000, v18
	v_and_b32_e32 v25, 0xffff0000, v16
	s_waitcnt lgkmcnt(0)
	v_pk_mul_f32 v[0:1], v[0:1], v[24:25]
	v_add_f32_e32 v13, 1.0, v13
	v_rcp_f32_e32 v22, v13
	v_mul_f32_e32 v13, 0xbfb8aa3b, v21
	v_exp_f32_e32 v13, v13
	v_lshlrev_b32_e32 v18, 16, v19
	v_and_b32_e32 v19, 0xffff0000, v19
	v_add_f32_e32 v13, 1.0, v13
	v_rcp_f32_e32 v23, v13
	s_nop 0
	v_pk_mul_f32 v[20:21], v[22:23], v[20:21]
	s_nop 0
	v_pk_mul_f32 v[0:1], v[0:1], v[20:21]
	v_lshlrev_b32_e32 v20, 16, v17
	v_cvt_pk_bf16_f32 v0, v0, v1
	v_mul_f32_e32 v1, 0xbfb8aa3b, v18
	v_exp_f32_e32 v1, v1
	v_and_b32_e32 v21, 0xffff0000, v17
	v_pk_mul_f32 v[2:3], v[2:3], v[20:21]
	v_add_f32_e32 v1, 1.0, v1
	v_rcp_f32_e32 v16, v1
	v_mul_f32_e32 v1, 0xbfb8aa3b, v19
	v_exp_f32_e32 v1, v1
	s_nop 0
	v_add_f32_e32 v1, 1.0, v1
	v_rcp_f32_e32 v17, v1
	s_nop 0
	v_pk_mul_f32 v[16:17], v[16:17], v[18:19]
	s_nop 0
	v_pk_mul_f32 v[2:3], v[2:3], v[16:17]
	s_nop 0
	v_cvt_pk_bf16_f32 v1, v2, v3
	global_store_dwordx2 v[14:15], v[0:1], off offset:256
	v_lshl_add_u64 v[14:15], v[4:5], 0, s[0:1]
	v_add_co_u32_e32 v14, vcc, s80, v14
	ds_read_b128 v[0:3], v12 offset:3264
	s_nop 0
	v_addc_co_u32_e32 v15, vcc, 0, v15, vcc
	s_add_u32 s0, s0, 0x18800
	s_addc_u32 s1, s1, 0
	v_add_u32_e32 v12, 0x1100, v12
	s_cmp_lg_u32 s0, 0x31000
	s_waitcnt vmcnt(8)
	v_mov_b32_e32 v16, v128
	v_mov_b32_e32 v17, v129
	v_lshlrev_b32_e32 v24, 16, v16
	s_waitcnt vmcnt(7)
	v_mov_b32_e32 v18, v130
	v_mov_b32_e32 v19, v131
	v_lshlrev_b32_e32 v20, 16, v18
	v_mul_f32_e32 v13, 0xbfb8aa3b, v20
	v_exp_f32_e32 v13, v13
	v_and_b32_e32 v21, 0xffff0000, v18
	v_and_b32_e32 v25, 0xffff0000, v16
	s_waitcnt lgkmcnt(0)
	v_pk_mul_f32 v[0:1], v[0:1], v[24:25]
	v_add_f32_e32 v13, 1.0, v13
	v_rcp_f32_e32 v22, v13
	v_mul_f32_e32 v13, 0xbfb8aa3b, v21
	v_exp_f32_e32 v13, v13
	v_lshlrev_b32_e32 v18, 16, v19
	v_and_b32_e32 v19, 0xffff0000, v19
	v_add_f32_e32 v13, 1.0, v13
	v_rcp_f32_e32 v23, v13
	s_nop 0
	v_pk_mul_f32 v[20:21], v[22:23], v[20:21]
	s_nop 0
	v_pk_mul_f32 v[0:1], v[0:1], v[20:21]
	v_lshlrev_b32_e32 v20, 16, v17
	v_cvt_pk_bf16_f32 v0, v0, v1
	v_mul_f32_e32 v1, 0xbfb8aa3b, v18
	v_exp_f32_e32 v1, v1
	v_and_b32_e32 v21, 0xffff0000, v17
	v_pk_mul_f32 v[2:3], v[2:3], v[20:21]
	v_add_f32_e32 v1, 1.0, v1
	v_rcp_f32_e32 v16, v1
	v_mul_f32_e32 v1, 0xbfb8aa3b, v19
	v_exp_f32_e32 v1, v1
	s_nop 0
	v_add_f32_e32 v1, 1.0, v1
	v_rcp_f32_e32 v17, v1
	s_nop 0
	v_pk_mul_f32 v[16:17], v[16:17], v[18:19]
	s_nop 0
	v_pk_mul_f32 v[2:3], v[2:3], v[16:17]
	s_nop 0
	v_cvt_pk_bf16_f32 v1, v2, v3
	global_store_dwordx2 v[14:15], v[0:1], off offset:256
	s_barrier
